# barrier v3 plus: this CU's L1 invalidate (buffer_inv sc1) issued right after arriving, before the spin, so it overlaps the wait
# speedup vs baseline: 1.0432x; 1.0086x over previous
.Lgb_done_s0:
.LBB0_69:
	s_or_b64 exec, exec, s[2:3]
	s_waitcnt vmcnt(0)
